# gate/up GEMM phases: epilogue alignment of the two wave halves removed (each half's silu epilogue now overlaps the other half's MMA block instead of both halves running VALU-bound epilogues together)
# baseline (speedup 1.0000x reference)
.Lalign_1:
	s_waitcnt vmcnt(0)
	v_fmamk_f32 v167, v167, 0x3a800000, v166
	v_rsq_f32_e32 v168, v167
	v_fmamk_f32 v159, v159, 0x3a800000, v166
	v_pk_mul_f32 v[124:125], v[124:125], v[168:169] op_sel_hi:[1,0]
	v_pk_mul_f32 v[126:127], v[126:127], v[168:169] op_sel_hi:[1,0]
	v_pk_mul_f32 v[120:121], v[120:121], v[168:169] op_sel_hi:[1,0]
	v_pk_mul_f32 v[122:123], v[122:123], v[168:169] op_sel_hi:[1,0]
	v_rsq_f32_e32 v172, v159
	v_pk_mul_f32 v[116:117], v[116:117], v[168:169] op_sel_hi:[1,0]
	v_pk_mul_f32 v[118:119], v[118:119], v[168:169] op_sel_hi:[1,0]
	v_pk_mul_f32 v[112:113], v[112:113], v[168:169] op_sel_hi:[1,0]
	v_pk_mul_f32 v[114:115], v[114:115], v[168:169] op_sel_hi:[1,0]
	v_mul_f32_e32 v159, 0xbfb8aa3b, v124
	v_mul_f32_e32 v167, 0xbfb8aa3b, v125
	v_mul_f32_e32 v168, 0xbfb8aa3b, v126
	v_mul_f32_e32 v169, 0xbfb8aa3b, v127
	v_mul_f32_e32 v173, 0xbfb8aa3b, v120
	v_mul_f32_e32 v174, 0xbfb8aa3b, v121
	v_mul_f32_e32 v175, 0xbfb8aa3b, v122
	v_mul_f32_e32 v176, 0xbfb8aa3b, v123
	v_exp_f32_e32 v159, v159
	v_exp_f32_e32 v167, v167
	v_exp_f32_e32 v168, v168
	v_exp_f32_e32 v169, v169
	v_exp_f32_e32 v173, v173
	v_exp_f32_e32 v174, v174
	v_exp_f32_e32 v175, v175
	v_exp_f32_e32 v176, v176
	v_add_f32_e32 v159, 1.0, v159
	v_add_f32_e32 v167, 1.0, v167
	v_add_f32_e32 v177, 1.0, v168
	v_add_f32_e32 v178, 1.0, v169
	v_add_f32_e32 v173, 1.0, v173
	v_add_f32_e32 v179, 1.0, v174
	v_add_f32_e32 v180, 1.0, v175
	v_add_f32_e32 v181, 1.0, v176
	v_rcp_f32_e32 v168, v159
	v_rcp_f32_e32 v169, v167
	v_rcp_f32_e32 v174, v177
	v_rcp_f32_e32 v175, v178
	v_rcp_f32_e32 v176, v173
	v_rcp_f32_e32 v177, v179
	v_rcp_f32_e32 v178, v180
	v_rcp_f32_e32 v179, v181
	v_pk_mul_f32 v[124:125], v[124:125], v[168:169]
	v_pk_mul_f32 v[126:127], v[126:127], v[174:175]
	v_pk_mul_f32 v[120:121], v[120:121], v[176:177]
	v_pk_mul_f32 v[122:123], v[122:123], v[178:179]
	v_pk_mul_f32 v[116:117], v[116:117], v[124:125]
	v_pk_mul_f32 v[118:119], v[118:119], v[126:127]
	v_pk_mul_f32 v[120:121], v[112:113], v[120:121]
	v_pk_mul_f32 v[122:123], v[114:115], v[122:123]
	v_cvt_pk_bf16_f32 v112, v116, v117
	v_cvt_pk_bf16_f32 v113, v118, v119
	v_cvt_pk_bf16_f32 v114, v120, v121
	v_cvt_pk_bf16_f32 v115, v122, v123
	v_pk_mul_f32 v[108:109], v[108:109], v[172:173] op_sel_hi:[1,0]
	global_store_dwordx4 v[170:171], v[112:115], off
	v_mul_f32_e32 v116, 0xbfb8aa3b, v108
	v_pk_mul_f32 v[110:111], v[110:111], v[172:173] op_sel_hi:[1,0]
	v_mul_f32_e32 v112, 0xbfb8aa3b, v109
	v_exp_f32_e32 v116, v116
	v_exp_f32_e32 v113, v112
	v_mul_f32_e32 v114, 0xbfb8aa3b, v110
	v_mul_f32_e32 v115, 0xbfb8aa3b, v111
	v_exp_f32_e32 v114, v114
	v_exp_f32_e32 v115, v115
	v_add_f32_e32 v112, 1.0, v116
	v_add_f32_e32 v113, 1.0, v113
	v_rcp_f32_e32 v112, v112
	v_rcp_f32_e32 v113, v113
	v_add_f32_e32 v114, 1.0, v114
	v_add_f32_e32 v115, 1.0, v115
	v_rcp_f32_e32 v114, v114
	v_rcp_f32_e32 v115, v115
	v_pk_mul_f32 v[100:101], v[100:101], v[172:173] op_sel_hi:[1,0]
	v_pk_mul_f32 v[108:109], v[108:109], v[112:113]
	v_pk_mul_f32 v[104:105], v[104:105], v[172:173] op_sel_hi:[1,0]
	v_pk_mul_f32 v[100:101], v[100:101], v[108:109]
	v_pk_mul_f32 v[108:109], v[110:111], v[114:115]
	v_mul_f32_e32 v110, 0xbfb8aa3b, v104
	v_exp_f32_e32 v110, v110
	v_pk_mul_f32 v[102:103], v[102:103], v[172:173] op_sel_hi:[1,0]
	v_pk_mul_f32 v[106:107], v[106:107], v[172:173] op_sel_hi:[1,0]
	v_pk_mul_f32 v[102:103], v[102:103], v[108:109]
	v_mul_f32_e32 v108, 0xbfb8aa3b, v105
	v_exp_f32_e32 v109, v108
	v_add_f32_e32 v108, 1.0, v110
	v_mul_f32_e32 v110, 0xbfb8aa3b, v106
	v_mul_f32_e32 v111, 0xbfb8aa3b, v107
	v_exp_f32_e32 v110, v110
	v_exp_f32_e32 v111, v111
	v_add_f32_e32 v109, 1.0, v109
	v_rcp_f32_e32 v108, v108
	v_rcp_f32_e32 v109, v109
	v_add_f32_e32 v110, 1.0, v110
	v_add_f32_e32 v111, 1.0, v111
	v_rcp_f32_e32 v110, v110
	v_rcp_f32_e32 v111, v111
	v_pk_mul_f32 v[96:97], v[96:97], v[172:173] op_sel_hi:[1,0]
	v_pk_mul_f32 v[104:105], v[104:105], v[108:109]
	s_nop 0
	v_pk_mul_f32 v[104:105], v[96:97], v[104:105]
	v_pk_mul_f32 v[96:97], v[98:99], v[172:173] op_sel_hi:[1,0]
	v_pk_mul_f32 v[98:99], v[106:107], v[110:111]
	s_nop 0
	v_pk_mul_f32 v[106:107], v[96:97], v[98:99]
	v_mad_i64_i32 v[96:97], s[36:37], v158, s61, v[144:145]
	v_lshl_add_u64 v[96:97], v[96:97], 0, s[30:31]
	v_lshl_add_u64 v[96:97], v[96:97], 0, s[20:21]
	v_lshl_add_u64 v[108:109], v[96:97], 0, v[148:149]
	v_fmamk_f32 v97, v153, 0x3a800000, v166
	v_cvt_pk_bf16_f32 v96, v100, v101
	v_rsq_f32_e32 v100, v97
	v_cvt_pk_bf16_f32 v97, v102, v103
	v_cvt_pk_bf16_f32 v98, v104, v105
	v_cvt_pk_bf16_f32 v99, v106, v107
	v_pk_mul_f32 v[92:93], v[92:93], v[100:101] op_sel_hi:[1,0]
	global_store_dwordx4 v[108:109], v[96:99], off
	v_mul_f32_e32 v101, 0xbfb8aa3b, v92
	v_exp_f32_e32 v101, v101
	v_mul_f32_e32 v96, 0xbfb8aa3b, v93
	v_exp_f32_e32 v97, v96
	v_pk_mul_f32 v[94:95], v[94:95], v[100:101] op_sel_hi:[1,0]
	s_nop 0
	v_mul_f32_e32 v98, 0xbfb8aa3b, v94
	v_mul_f32_e32 v99, 0xbfb8aa3b, v95
	v_exp_f32_e32 v98, v98
	v_exp_f32_e32 v99, v99
	v_add_f32_e32 v96, 1.0, v101
	v_add_f32_e32 v97, 1.0, v97
	v_rcp_f32_e32 v96, v96
	v_rcp_f32_e32 v97, v97
	v_add_f32_e32 v98, 1.0, v98
	v_add_f32_e32 v99, 1.0, v99
	v_rcp_f32_e32 v98, v98
	v_rcp_f32_e32 v99, v99
	v_pk_mul_f32 v[84:85], v[84:85], v[100:101] op_sel_hi:[1,0]
	v_pk_mul_f32 v[92:93], v[92:93], v[96:97]
	v_pk_mul_f32 v[88:89], v[88:89], v[100:101] op_sel_hi:[1,0]
	v_pk_mul_f32 v[84:85], v[84:85], v[92:93]
	v_pk_mul_f32 v[92:93], v[94:95], v[98:99]
	v_mul_f32_e32 v94, 0xbfb8aa3b, v88
	v_exp_f32_e32 v94, v94
	v_pk_mul_f32 v[86:87], v[86:87], v[100:101] op_sel_hi:[1,0]
	v_pk_mul_f32 v[90:91], v[90:91], v[100:101] op_sel_hi:[1,0]
	v_pk_mul_f32 v[86:87], v[86:87], v[92:93]
	v_mul_f32_e32 v92, 0xbfb8aa3b, v89
	v_exp_f32_e32 v93, v92
	v_add_f32_e32 v92, 1.0, v94
	v_mul_f32_e32 v94, 0xbfb8aa3b, v90
	v_mul_f32_e32 v95, 0xbfb8aa3b, v91
	v_exp_f32_e32 v94, v94
	v_exp_f32_e32 v95, v95
	v_add_f32_e32 v93, 1.0, v93
	v_rcp_f32_e32 v92, v92
	v_rcp_f32_e32 v93, v93
	v_add_f32_e32 v94, 1.0, v94
	v_add_f32_e32 v95, 1.0, v95
	v_rcp_f32_e32 v94, v94
	v_rcp_f32_e32 v95, v95
	v_pk_mul_f32 v[80:81], v[80:81], v[100:101] op_sel_hi:[1,0]
	v_pk_mul_f32 v[88:89], v[88:89], v[92:93]
	s_nop 0
	v_pk_mul_f32 v[88:89], v[80:81], v[88:89]
	v_pk_mul_f32 v[80:81], v[82:83], v[100:101] op_sel_hi:[1,0]
	v_pk_mul_f32 v[82:83], v[90:91], v[94:95]
	s_nop 0
	v_pk_mul_f32 v[90:91], v[80:81], v[82:83]
	v_mad_i64_i32 v[80:81], s[36:37], v160, s61, v[144:145]
	v_lshl_add_u64 v[80:81], v[80:81], 0, s[30:31]
	v_lshl_add_u64 v[80:81], v[80:81], 0, s[20:21]
	v_lshl_add_u64 v[92:93], v[80:81], 0, v[148:149]
	v_fmamk_f32 v81, v155, 0x3a800000, v166
	v_cvt_pk_bf16_f32 v80, v84, v85
	v_rsq_f32_e32 v84, v81
	v_cvt_pk_bf16_f32 v81, v86, v87
	v_cvt_pk_bf16_f32 v82, v88, v89
	v_cvt_pk_bf16_f32 v83, v90, v91
	v_pk_mul_f32 v[76:77], v[76:77], v[84:85] op_sel_hi:[1,0]
	global_store_dwordx4 v[92:93], v[80:83], off
	v_mul_f32_e32 v85, 0xbfb8aa3b, v76
	v_exp_f32_e32 v85, v85
	v_mul_f32_e32 v80, 0xbfb8aa3b, v77
	v_exp_f32_e32 v81, v80
	v_pk_mul_f32 v[78:79], v[78:79], v[84:85] op_sel_hi:[1,0]
	s_nop 0
	v_mul_f32_e32 v82, 0xbfb8aa3b, v78
	v_mul_f32_e32 v83, 0xbfb8aa3b, v79
	v_exp_f32_e32 v82, v82
	v_exp_f32_e32 v83, v83
	v_add_f32_e32 v80, 1.0, v85
	v_add_f32_e32 v81, 1.0, v81
	v_rcp_f32_e32 v80, v80
	v_rcp_f32_e32 v81, v81
	v_add_f32_e32 v82, 1.0, v82
	v_add_f32_e32 v83, 1.0, v83
	v_rcp_f32_e32 v82, v82
	v_rcp_f32_e32 v83, v83
	v_pk_mul_f32 v[68:69], v[68:69], v[84:85] op_sel_hi:[1,0]
	v_pk_mul_f32 v[76:77], v[76:77], v[80:81]
	v_pk_mul_f32 v[72:73], v[72:73], v[84:85] op_sel_hi:[1,0]
	v_pk_mul_f32 v[68:69], v[68:69], v[76:77]
	v_pk_mul_f32 v[76:77], v[78:79], v[82:83]
	v_mul_f32_e32 v78, 0xbfb8aa3b, v72
	v_exp_f32_e32 v78, v78
	v_pk_mul_f32 v[70:71], v[70:71], v[84:85] op_sel_hi:[1,0]
	v_pk_mul_f32 v[74:75], v[74:75], v[84:85] op_sel_hi:[1,0]
	v_pk_mul_f32 v[70:71], v[70:71], v[76:77]
	v_mul_f32_e32 v76, 0xbfb8aa3b, v73
	v_exp_f32_e32 v77, v76
	v_add_f32_e32 v76, 1.0, v78
	v_mul_f32_e32 v78, 0xbfb8aa3b, v74
	v_mul_f32_e32 v79, 0xbfb8aa3b, v75
	v_exp_f32_e32 v78, v78
	v_exp_f32_e32 v79, v79
	v_add_f32_e32 v77, 1.0, v77
	v_rcp_f32_e32 v76, v76
	v_rcp_f32_e32 v77, v77
	v_add_f32_e32 v78, 1.0, v78
	v_add_f32_e32 v79, 1.0, v79
	v_rcp_f32_e32 v78, v78
	v_rcp_f32_e32 v79, v79
	v_pk_mul_f32 v[64:65], v[64:65], v[84:85] op_sel_hi:[1,0]
	v_pk_mul_f32 v[72:73], v[72:73], v[76:77]
	s_nop 0
	v_pk_mul_f32 v[72:73], v[64:65], v[72:73]
	v_pk_mul_f32 v[64:65], v[66:67], v[84:85] op_sel_hi:[1,0]
	v_pk_mul_f32 v[66:67], v[74:75], v[78:79]
	s_nop 0
	v_pk_mul_f32 v[74:75], v[64:65], v[66:67]
	v_mad_i64_i32 v[64:65], s[36:37], v156, s61, v[144:145]
	v_lshl_add_u64 v[64:65], v[64:65], 0, s[30:31]
	v_lshl_add_u64 v[64:65], v[64:65], 0, s[20:21]
	v_fmamk_f32 v66, v157, 0x3a800000, v166
	v_lshl_add_u64 v[76:77], v[64:65], 0, v[148:149]
	v_cvt_pk_bf16_f32 v64, v68, v69
	v_rsq_f32_e32 v68, v66
	v_cvt_pk_bf16_f32 v65, v70, v71
	v_cvt_pk_bf16_f32 v66, v72, v73
	v_cvt_pk_bf16_f32 v67, v74, v75
	v_pk_mul_f32 v[60:61], v[60:61], v[68:69] op_sel_hi:[1,0]
	global_store_dwordx4 v[76:77], v[64:67], off
	v_pk_mul_f32 v[62:63], v[62:63], v[68:69] op_sel_hi:[1,0]
	v_pk_mul_f32 v[52:53], v[52:53], v[68:69] op_sel_hi:[1,0]
	v_mul_f32_e32 v64, 0xbfb8aa3b, v60
	v_mul_f32_e32 v65, 0xbfb8aa3b, v61
	v_exp_f32_e32 v64, v64
	v_exp_f32_e32 v65, v65
	v_mul_f32_e32 v66, 0xbfb8aa3b, v62
	v_mul_f32_e32 v67, 0xbfb8aa3b, v63
	v_exp_f32_e32 v66, v66
	v_exp_f32_e32 v67, v67
	v_add_f32_e32 v64, 1.0, v64
	v_add_f32_e32 v65, 1.0, v65
	v_rcp_f32_e32 v64, v64
	v_rcp_f32_e32 v65, v65
	v_add_f32_e32 v66, 1.0, v66
	v_add_f32_e32 v67, 1.0, v67
	v_rcp_f32_e32 v66, v66
	v_rcp_f32_e32 v67, v67
	v_pk_mul_f32 v[60:61], v[60:61], v[64:65]
	v_pk_mul_f32 v[56:57], v[56:57], v[68:69] op_sel_hi:[1,0]
	v_pk_mul_f32 v[52:53], v[52:53], v[60:61]
	v_pk_mul_f32 v[60:61], v[62:63], v[66:67]
	v_mul_f32_e32 v62, 0xbfb8aa3b, v56
	v_exp_f32_e32 v62, v62
	v_pk_mul_f32 v[54:55], v[54:55], v[68:69] op_sel_hi:[1,0]
	v_pk_mul_f32 v[58:59], v[58:59], v[68:69] op_sel_hi:[1,0]
	v_pk_mul_f32 v[54:55], v[54:55], v[60:61]
	v_mul_f32_e32 v60, 0xbfb8aa3b, v57
	v_exp_f32_e32 v61, v60
	v_add_f32_e32 v60, 1.0, v62
	v_mul_f32_e32 v62, 0xbfb8aa3b, v58
	v_mul_f32_e32 v63, 0xbfb8aa3b, v59
	v_exp_f32_e32 v62, v62
	v_exp_f32_e32 v63, v63
	v_add_f32_e32 v61, 1.0, v61
	v_rcp_f32_e32 v60, v60
	v_rcp_f32_e32 v61, v61
	v_add_f32_e32 v62, 1.0, v62
	v_add_f32_e32 v63, 1.0, v63
	v_rcp_f32_e32 v62, v62
	v_rcp_f32_e32 v63, v63
	v_pk_mul_f32 v[48:49], v[48:49], v[68:69] op_sel_hi:[1,0]
	v_pk_mul_f32 v[56:57], v[56:57], v[60:61]
	s_nop 0
	v_pk_mul_f32 v[56:57], v[48:49], v[56:57]
	v_pk_mul_f32 v[48:49], v[50:51], v[68:69] op_sel_hi:[1,0]
	v_pk_mul_f32 v[50:51], v[58:59], v[62:63]
	s_nop 0
	v_pk_mul_f32 v[58:59], v[48:49], v[50:51]
	v_mad_i64_i32 v[48:49], s[36:37], v154, s61, v[144:145]
	v_lshl_add_u64 v[48:49], v[48:49], 0, s[30:31]
	v_lshl_add_u64 v[48:49], v[48:49], 0, s[20:21]
	v_lshl_add_u64 v[60:61], v[48:49], 0, v[148:149]
	v_fmamk_f32 v49, v161, 0x3a800000, v166
	v_cvt_pk_bf16_f32 v48, v52, v53
	v_rsq_f32_e32 v52, v49
	v_cvt_pk_bf16_f32 v49, v54, v55
	v_cvt_pk_bf16_f32 v50, v56, v57
	v_cvt_pk_bf16_f32 v51, v58, v59
	v_pk_mul_f32 v[44:45], v[44:45], v[52:53] op_sel_hi:[1,0]
	global_store_dwordx4 v[60:61], v[48:51], off
	v_mul_f32_e32 v53, 0xbfb8aa3b, v44
	v_exp_f32_e32 v53, v53
	v_mul_f32_e32 v48, 0xbfb8aa3b, v45
	v_exp_f32_e32 v49, v48
	v_pk_mul_f32 v[46:47], v[46:47], v[52:53] op_sel_hi:[1,0]
	s_nop 0
	v_mul_f32_e32 v50, 0xbfb8aa3b, v46
	v_mul_f32_e32 v51, 0xbfb8aa3b, v47
	v_exp_f32_e32 v50, v50
	v_exp_f32_e32 v51, v51
	v_add_f32_e32 v48, 1.0, v53
	v_add_f32_e32 v49, 1.0, v49
	v_rcp_f32_e32 v48, v48
	v_rcp_f32_e32 v49, v49
	v_add_f32_e32 v50, 1.0, v50
	v_add_f32_e32 v51, 1.0, v51
	v_rcp_f32_e32 v50, v50
	v_rcp_f32_e32 v51, v51
	v_pk_mul_f32 v[36:37], v[36:37], v[52:53] op_sel_hi:[1,0]
	v_pk_mul_f32 v[44:45], v[44:45], v[48:49]
	v_pk_mul_f32 v[40:41], v[40:41], v[52:53] op_sel_hi:[1,0]
	v_pk_mul_f32 v[36:37], v[36:37], v[44:45]
	v_pk_mul_f32 v[44:45], v[46:47], v[50:51]
	v_mul_f32_e32 v46, 0xbfb8aa3b, v40
	v_exp_f32_e32 v46, v46
	v_pk_mul_f32 v[38:39], v[38:39], v[52:53] op_sel_hi:[1,0]
	v_pk_mul_f32 v[42:43], v[42:43], v[52:53] op_sel_hi:[1,0]
	v_pk_mul_f32 v[38:39], v[38:39], v[44:45]
	v_mul_f32_e32 v44, 0xbfb8aa3b, v41
	v_exp_f32_e32 v45, v44
	v_add_f32_e32 v44, 1.0, v46
	v_mul_f32_e32 v46, 0xbfb8aa3b, v42
	v_mul_f32_e32 v47, 0xbfb8aa3b, v43
	v_exp_f32_e32 v46, v46
	v_exp_f32_e32 v47, v47
	v_add_f32_e32 v45, 1.0, v45
	v_rcp_f32_e32 v44, v44
	v_rcp_f32_e32 v45, v45
	v_add_f32_e32 v46, 1.0, v46
	v_add_f32_e32 v47, 1.0, v47
	v_rcp_f32_e32 v46, v46
	v_rcp_f32_e32 v47, v47
	v_pk_mul_f32 v[32:33], v[32:33], v[52:53] op_sel_hi:[1,0]
	v_pk_mul_f32 v[40:41], v[40:41], v[44:45]
	s_nop 0
	v_pk_mul_f32 v[40:41], v[32:33], v[40:41]
	v_pk_mul_f32 v[32:33], v[34:35], v[52:53] op_sel_hi:[1,0]
	v_pk_mul_f32 v[34:35], v[42:43], v[46:47]
	s_nop 0
	v_pk_mul_f32 v[42:43], v[32:33], v[34:35]
	v_mad_i64_i32 v[32:33], s[36:37], v152, s61, v[144:145]
	v_lshl_add_u64 v[32:33], v[32:33], 0, s[30:31]
	v_lshl_add_u64 v[32:33], v[32:33], 0, s[20:21]
	v_lshl_add_u64 v[44:45], v[32:33], 0, v[148:149]
	v_fmamk_f32 v33, v151, 0x3a800000, v166
	v_cvt_pk_bf16_f32 v32, v36, v37
	v_rsq_f32_e32 v36, v33
	v_cvt_pk_bf16_f32 v33, v38, v39
	v_cvt_pk_bf16_f32 v34, v40, v41
	v_cvt_pk_bf16_f32 v35, v42, v43
	v_pk_mul_f32 v[28:29], v[28:29], v[36:37] op_sel_hi:[1,0]
	global_store_dwordx4 v[44:45], v[32:35], off
	v_mul_f32_e32 v37, 0xbfb8aa3b, v28
	v_exp_f32_e32 v37, v37
	v_mul_f32_e32 v32, 0xbfb8aa3b, v29
	v_exp_f32_e32 v33, v32
	v_pk_mul_f32 v[30:31], v[30:31], v[36:37] op_sel_hi:[1,0]
	s_nop 0
	v_mul_f32_e32 v34, 0xbfb8aa3b, v30
	v_mul_f32_e32 v35, 0xbfb8aa3b, v31
	v_exp_f32_e32 v34, v34
	v_exp_f32_e32 v35, v35
	v_add_f32_e32 v32, 1.0, v37
	v_add_f32_e32 v33, 1.0, v33
	v_rcp_f32_e32 v32, v32
	v_rcp_f32_e32 v33, v33
	v_add_f32_e32 v34, 1.0, v34
	v_add_f32_e32 v35, 1.0, v35
	v_rcp_f32_e32 v34, v34
	v_rcp_f32_e32 v35, v35
	v_pk_mul_f32 v[20:21], v[20:21], v[36:37] op_sel_hi:[1,0]
	v_pk_mul_f32 v[28:29], v[28:29], v[32:33]
	v_pk_mul_f32 v[24:25], v[24:25], v[36:37] op_sel_hi:[1,0]
	v_pk_mul_f32 v[20:21], v[20:21], v[28:29]
	v_pk_mul_f32 v[28:29], v[30:31], v[34:35]
	v_mul_f32_e32 v30, 0xbfb8aa3b, v24
	v_exp_f32_e32 v30, v30
	v_pk_mul_f32 v[22:23], v[22:23], v[36:37] op_sel_hi:[1,0]
	v_pk_mul_f32 v[26:27], v[26:27], v[36:37] op_sel_hi:[1,0]
	v_pk_mul_f32 v[22:23], v[22:23], v[28:29]
	v_mul_f32_e32 v28, 0xbfb8aa3b, v25
	v_exp_f32_e32 v29, v28
	v_add_f32_e32 v28, 1.0, v30
	v_mul_f32_e32 v30, 0xbfb8aa3b, v26
	v_mul_f32_e32 v31, 0xbfb8aa3b, v27
	v_exp_f32_e32 v30, v30
	v_exp_f32_e32 v31, v31
	v_add_f32_e32 v29, 1.0, v29
	v_rcp_f32_e32 v28, v28
	v_rcp_f32_e32 v29, v29
	v_add_f32_e32 v30, 1.0, v30
	v_add_f32_e32 v31, 1.0, v31
	v_rcp_f32_e32 v30, v30
	v_rcp_f32_e32 v31, v31
	v_pk_mul_f32 v[16:17], v[16:17], v[36:37] op_sel_hi:[1,0]
	v_pk_mul_f32 v[24:25], v[24:25], v[28:29]
	s_nop 0
	v_pk_mul_f32 v[24:25], v[16:17], v[24:25]
	v_pk_mul_f32 v[16:17], v[18:19], v[36:37] op_sel_hi:[1,0]
	v_pk_mul_f32 v[18:19], v[26:27], v[30:31]
	s_nop 0
	v_pk_mul_f32 v[26:27], v[16:17], v[18:19]
	v_mad_i64_i32 v[16:17], s[36:37], v150, s61, v[144:145]
	v_lshl_add_u64 v[16:17], v[16:17], 0, s[30:31]
	v_lshl_add_u64 v[16:17], v[16:17], 0, s[20:21]
	v_lshl_add_u64 v[28:29], v[16:17], 0, v[148:149]
	v_fmamk_f32 v17, v147, 0x3a800000, v166
	v_cvt_pk_bf16_f32 v16, v20, v21
	v_rsq_f32_e32 v20, v17
	v_cvt_pk_bf16_f32 v17, v22, v23
	v_cvt_pk_bf16_f32 v18, v24, v25
	v_cvt_pk_bf16_f32 v19, v26, v27
	v_pk_mul_f32 v[12:13], v[12:13], v[20:21] op_sel_hi:[1,0]
	global_store_dwordx4 v[28:29], v[16:19], off
	v_mul_f32_e32 v21, 0xbfb8aa3b, v12
	v_exp_f32_e32 v21, v21
	v_mul_f32_e32 v16, 0xbfb8aa3b, v13
	v_exp_f32_e32 v17, v16
	v_pk_mul_f32 v[14:15], v[14:15], v[20:21] op_sel_hi:[1,0]
	s_nop 0
	v_mul_f32_e32 v18, 0xbfb8aa3b, v14
	v_mul_f32_e32 v19, 0xbfb8aa3b, v15
	v_exp_f32_e32 v18, v18
	v_exp_f32_e32 v19, v19
	v_add_f32_e32 v16, 1.0, v21
	v_add_f32_e32 v17, 1.0, v17
	v_rcp_f32_e32 v16, v16
	v_rcp_f32_e32 v17, v17
	v_add_f32_e32 v18, 1.0, v18
	v_add_f32_e32 v19, 1.0, v19
	v_rcp_f32_e32 v18, v18
	v_rcp_f32_e32 v19, v19
	v_pk_mul_f32 v[4:5], v[4:5], v[20:21] op_sel_hi:[1,0]
	v_pk_mul_f32 v[12:13], v[12:13], v[16:17]
	v_pk_mul_f32 v[8:9], v[8:9], v[20:21] op_sel_hi:[1,0]
	v_pk_mul_f32 v[4:5], v[4:5], v[12:13]
	v_pk_mul_f32 v[12:13], v[14:15], v[18:19]
	v_mul_f32_e32 v14, 0xbfb8aa3b, v8
	v_exp_f32_e32 v14, v14
	v_pk_mul_f32 v[6:7], v[6:7], v[20:21] op_sel_hi:[1,0]
	v_pk_mul_f32 v[10:11], v[10:11], v[20:21] op_sel_hi:[1,0]
	v_pk_mul_f32 v[6:7], v[6:7], v[12:13]
	v_mul_f32_e32 v12, 0xbfb8aa3b, v9
	v_exp_f32_e32 v13, v12
	v_add_f32_e32 v12, 1.0, v14
	v_mul_f32_e32 v14, 0xbfb8aa3b, v10
	v_mul_f32_e32 v15, 0xbfb8aa3b, v11
	v_exp_f32_e32 v14, v14
	v_exp_f32_e32 v15, v15
	v_add_f32_e32 v13, 1.0, v13
	v_rcp_f32_e32 v12, v12
	v_rcp_f32_e32 v13, v13
	v_add_f32_e32 v14, 1.0, v14
	v_add_f32_e32 v15, 1.0, v15
	v_rcp_f32_e32 v14, v14
	v_rcp_f32_e32 v15, v15
	v_pk_mul_f32 v[0:1], v[0:1], v[20:21] op_sel_hi:[1,0]
	v_pk_mul_f32 v[8:9], v[8:9], v[12:13]
	s_nop 0
	v_pk_mul_f32 v[8:9], v[0:1], v[8:9]
	v_pk_mul_f32 v[0:1], v[2:3], v[20:21] op_sel_hi:[1,0]
	v_pk_mul_f32 v[2:3], v[10:11], v[14:15]
	s_nop 0
	v_pk_mul_f32 v[10:11], v[0:1], v[2:3]
	v_mad_i64_i32 v[0:1], s[36:37], v146, s61, v[144:145]
	v_lshl_add_u64 v[0:1], v[0:1], 0, s[30:31]
	v_lshl_add_u64 v[0:1], v[0:1], 0, s[20:21]
	v_lshl_add_u64 v[12:13], v[0:1], 0, v[148:149]
	v_cvt_pk_bf16_f32 v0, v4, v5
	v_cvt_pk_bf16_f32 v1, v6, v7
	v_cvt_pk_bf16_f32 v2, v8, v9
	v_cvt_pk_bf16_f32 v3, v10, v11
	global_store_dwordx4 v[12:13], v[0:3], off
	s_cbranch_vccnz .LBB0_780
	s_andn2_b64 vcc, exec, s[8:9]
	s_cbranch_vccnz .LBB0_779
	s_branch .LBB0_779
.LBB0_790:
	s_cmp_lg_u64 s[8:9], 0
	s_cbranch_scc1 .Lnoalign_fin_1
	s_barrier
